# grid barrier: all waiters poll the arrival counter TOP >= (gen+1)*nx; TOPGEN add and XGEN relay removed
# speedup vs baseline: 1.0191x; 1.0021x over previous
; DI unsigned xb_ld(unsigned* p)              { return __hip_atomic_load(p, __ATOMIC_RELAXED, __HIP_MEMORY_SCOPE_AGENT); }
; DI unsigned xb_add(unsigned* p, unsigned v) { return __hip_atomic_fetch_add(p, v, __ATOMIC_RELAXED, __HIP_MEMORY_SCOPE_AGENT); }
; #define XB_SPIN(cond, bar) do { unsigned _sp = 0; while (cond) { __builtin_amdgcn_s_sleep(1); \
;     if ((++_sp & 255u) == 0u) { if (xb_ld(&(bar)[XB_TMO])) break; if (_sp > XB_SPIN_CAP) { atomicAdd(&(bar)[XB_TMO], 1u); break; } } } } while (0)
; DI void xcd_barrier(const XcdBarrier& b) {
;     ...
;     const unsigned old = xb_add(&bar[XB_XSUB(b.x)], 1u);
;     const unsigned gen = old / nloc;
;     if (old + 1u == (gen + 1u) * nloc) {
;       __builtin_amdgcn_fence(__ATOMIC_RELEASE, "agent");
;       asm volatile("s_waitcnt vmcnt(0)" ::: "memory");
;       const unsigned og = xb_add(&bar[XB_TOP], 1u);
;       const unsigned tg = og / nx;
;       if (og + 1u == (tg + 1u) * nx) xb_add(&bar[XB_TOPGEN], 1u);
;       else XB_SPIN(xb_ld(&bar[XB_TOPGEN]) == tg, bar);
;       __builtin_amdgcn_fence(__ATOMIC_ACQUIRE, "agent");
;       xb_add(&bar[XB_XGEN(b.x)], 1u);
;       asm volatile("s_waitcnt vmcnt(0)" ::: "memory");
;     } else {
;       XB_SPIN(xb_ld(&bar[XB_XGEN(b.x)]) == gen, bar);
.LBB0_65:
	s_or_b64 exec, exec, s[12:13]
	v_cvt_f32_u32_e32 v4, v2
	s_waitcnt vmcnt(0)
	v_readfirstlane_b32 s0, v3
	v_sub_u32_e32 v3, 0, v2
	v_rcp_iflag_f32_e32 v4, v4
	v_add_u32_e32 v5, s0, v1
	v_mul_f32_e32 v4, 0x4f7ffffe, v4
	v_cvt_u32_f32_e32 v4, v4
	v_mul_lo_u32 v1, v3, v4
	v_mul_hi_u32 v1, v4, v1
	v_add_u32_e32 v1, v4, v1
	v_mul_hi_u32 v1, v5, v1
	v_mul_lo_u32 v3, v1, v2
	v_sub_u32_e32 v3, v5, v3
	v_add_u32_e32 v4, 1, v1
	v_cmp_ge_u32_e32 vcc, v3, v2
	s_nop 1
	v_cndmask_b32_e32 v1, v1, v4, vcc
	v_sub_u32_e32 v4, v3, v2
	v_cndmask_b32_e32 v3, v3, v4, vcc
	v_add_u32_e32 v4, 1, v1
	v_cmp_ge_u32_e32 vcc, v3, v2
	v_add_u32_e32 v3, 1, v5
	s_nop 0
	v_cndmask_b32_e32 v1, v1, v4, vcc
	v_mul_lo_u32 v4, v2, v1
	v_add_u32_e32 v2, v4, v2
	v_cmp_ne_u32_e32 vcc, v3, v2
	s_and_saveexec_b64 s[0:1], vcc
	s_xor_b64 s[10:11], exec, s[0:1]
	s_cbranch_execz .LBB0_79
	s_waitcnt lgkmcnt(0)
	v_add_u32_e32 v1, 1, v1
	s_add_u32 s16, s22, 0x1c103400
	s_addc_u32 s17, s23, 0
	v_mul_lo_u32 v1, v1, v0
	v_mov_b32_e32 v0, 0
	global_load_dword v0, v0, s[16:17] sc1
	s_waitcnt vmcnt(0)
	v_cmp_lt_u32_e32 vcc, v0, v1
	s_and_saveexec_b64 s[12:13], vcc
	s_cbranch_execz .LBB0_78
	s_add_u32 s14, s22, 0x1c100200
	s_addc_u32 s15, s23, 0
	s_mov_b32 s0, 1
	s_mov_b64 s[18:19], 0
	v_mov_b32_e32 v0, 0
	s_branch .LBB0_69

; DI unsigned xb_ld(unsigned* p)              { return __hip_atomic_load(p, __ATOMIC_RELAXED, __HIP_MEMORY_SCOPE_AGENT); }
; #define XB_SPIN(cond, bar) do { unsigned _sp = 0; while (cond) { __builtin_amdgcn_s_sleep(1); \
;     if ((++_sp & 255u) == 0u) { if (xb_ld(&(bar)[XB_TMO])) break; if (_sp > XB_SPIN_CAP) { atomicAdd(&(bar)[XB_TMO], 1u); break; } } } } while (0)
; DI void xcd_barrier(const XcdBarrier& b) {
;     ...
;       XB_SPIN(xb_ld(&bar[XB_XGEN(b.x)]) == gen, bar);
.LBB0_73:
	global_load_dword v2, v0, s[16:17] sc1
	s_add_i32 s0, s0, 1
	s_mov_b64 s[30:31], -1
	s_waitcnt vmcnt(0)
	v_cmp_ge_u32_e32 vcc, v2, v1
	s_orn2_b64 s[28:29], vcc, exec
	s_branch .LBB0_68

; DI unsigned xb_ld(unsigned* p)              { return __hip_atomic_load(p, __ATOMIC_RELAXED, __HIP_MEMORY_SCOPE_AGENT); }
; DI unsigned xb_add(unsigned* p, unsigned v) { return __hip_atomic_fetch_add(p, v, __ATOMIC_RELAXED, __HIP_MEMORY_SCOPE_AGENT); }
; #define XB_SPIN(cond, bar) do { unsigned _sp = 0; while (cond) { __builtin_amdgcn_s_sleep(1); \
;     if ((++_sp & 255u) == 0u) { if (xb_ld(&(bar)[XB_TMO])) break; if (_sp > XB_SPIN_CAP) { atomicAdd(&(bar)[XB_TMO], 1u); break; } } } } while (0)
; DI void xcd_barrier(const XcdBarrier& b) {
;     ...
;       const unsigned og = xb_add(&bar[XB_TOP], 1u);
;       const unsigned tg = og / nx;
;       if (og + 1u == (tg + 1u) * nx) xb_add(&bar[XB_TOPGEN], 1u);
;       else XB_SPIN(xb_ld(&bar[XB_TOPGEN]) == tg, bar);
.LBB0_82:
	s_or_b64 exec, exec, s[12:13]
	v_cvt_f32_u32_e32 v3, v0
	s_waitcnt vmcnt(0)
	v_readfirstlane_b32 s0, v2
	s_add_u32 s12, s22, 0x1c103500
	s_addc_u32 s13, s23, 0
	v_rcp_iflag_f32_e32 v3, v3
	v_add_u32_e32 v1, s0, v1
	v_add_u32_e32 v4, 1, v1
	s_mov_b64 s[14:15], 0
	v_mul_f32_e32 v2, 0x4f7ffffe, v3
	v_cvt_u32_f32_e32 v2, v2
	v_sub_u32_e32 v3, 0, v0
	v_mul_lo_u32 v3, v3, v2
	v_mul_hi_u32 v3, v2, v3
	v_add_u32_e32 v2, v2, v3
	v_mul_hi_u32 v2, v1, v2
	v_mul_lo_u32 v3, v2, v0
	v_sub_u32_e32 v1, v1, v3
	v_add_u32_e32 v5, 1, v2
	v_cmp_ge_u32_e32 vcc, v1, v0
	v_sub_u32_e32 v3, v1, v0
	s_nop 0
	v_cndmask_b32_e32 v2, v2, v5, vcc
	v_cndmask_b32_e32 v1, v1, v3, vcc
	v_add_u32_e32 v3, 1, v2
	v_cmp_ge_u32_e32 vcc, v1, v0
	s_nop 1
	v_cndmask_b32_e32 v2, v2, v3, vcc
	v_mul_lo_u32 v1, v0, v2
	v_add_u32_e32 v0, v1, v0
	v_cmp_ne_u32_e32 vcc, v4, v0
	v_mov_b32_e32 v2, v0
	v_mov_b64_e32 v[0:1], s[12:13]
	s_and_saveexec_b64 s[10:11], vcc
	s_cbranch_execz .LBB0_94
	v_mov_b32_e32 v0, 0
	global_load_dword v1, v0, s[12:13] offset:-256 sc1
	s_mov_b64 s[18:19], 0
	s_waitcnt vmcnt(0)
	v_cmp_lt_u32_e32 vcc, v1, v2
	s_and_saveexec_b64 s[16:17], vcc
	s_cbranch_execz .LBB0_93
	s_add_u32 s14, s22, 0x1c100200
	s_addc_u32 s15, s23, 0
	s_mov_b32 s0, 1
	s_branch .LBB0_86

; DI unsigned xb_ld(unsigned* p)              { return __hip_atomic_load(p, __ATOMIC_RELAXED, __HIP_MEMORY_SCOPE_AGENT); }
; #define XB_SPIN(cond, bar) do { unsigned _sp = 0; while (cond) { __builtin_amdgcn_s_sleep(1); \
;     if ((++_sp & 255u) == 0u) { if (xb_ld(&(bar)[XB_TMO])) break; if (_sp > XB_SPIN_CAP) { atomicAdd(&(bar)[XB_TMO], 1u); break; } } } } while (0)
; DI void xcd_barrier(const XcdBarrier& b) {
;     ...
;       else XB_SPIN(xb_ld(&bar[XB_TOPGEN]) == tg, bar);
.LBB0_90:
	global_load_dword v1, v0, s[12:13] offset:-256 sc1
	s_add_i32 s0, s0, 1
	s_mov_b64 s[28:29], -1
	s_waitcnt vmcnt(0)
	v_cmp_ge_u32_e32 vcc, v1, v2
	s_orn2_b64 s[34:35], vcc, exec
	s_branch .LBB0_85

; DI unsigned xb_ld(unsigned* p)              { return __hip_atomic_load(p, __ATOMIC_RELAXED, __HIP_MEMORY_SCOPE_AGENT); }
; #define XB_SPIN(cond, bar) do { unsigned _sp = 0; while (cond) { __builtin_amdgcn_s_sleep(1); \
;     if ((++_sp & 255u) == 0u) { if (xb_ld(&(bar)[XB_TMO])) break; if (_sp > XB_SPIN_CAP) { atomicAdd(&(bar)[XB_TMO], 1u); break; } } } } while (0)
; DI void xcd_barrier(const XcdBarrier& b) {
;     ...
;       XB_SPIN(xb_ld(&bar[XB_XGEN(b.x)]) == gen, bar);
.LBB0_376:
	global_load_dword v2, v0, s[16:17] sc1
	s_add_i32 s0, s0, 1
	s_mov_b64 s[34:35], -1
	s_waitcnt vmcnt(0)
	v_cmp_ge_u32_e32 vcc, v2, v1
	s_orn2_b64 s[30:31], vcc, exec
	s_branch .LBB0_371

; DI unsigned xb_ld(unsigned* p)              { return __hip_atomic_load(p, __ATOMIC_RELAXED, __HIP_MEMORY_SCOPE_AGENT); }
; #define XB_SPIN(cond, bar) do { unsigned _sp = 0; while (cond) { __builtin_amdgcn_s_sleep(1); \
;     if ((++_sp & 255u) == 0u) { if (xb_ld(&(bar)[XB_TMO])) break; if (_sp > XB_SPIN_CAP) { atomicAdd(&(bar)[XB_TMO], 1u); break; } } } } while (0)
; DI void xcd_barrier(const XcdBarrier& b) {
;     ...
;       else XB_SPIN(xb_ld(&bar[XB_TOPGEN]) == tg, bar);
.LBB0_393:
	global_load_dword v1, v0, s[12:13] offset:-256 sc1
	s_add_i32 s0, s0, 1
	s_mov_b64 s[30:31], -1
	s_waitcnt vmcnt(0)
	v_cmp_ge_u32_e32 vcc, v1, v2
	s_orn2_b64 s[38:39], vcc, exec
	s_branch .LBB0_388

; DI unsigned xb_ld(unsigned* p)              { return __hip_atomic_load(p, __ATOMIC_RELAXED, __HIP_MEMORY_SCOPE_AGENT); }
; DI unsigned xb_add(unsigned* p, unsigned v) { return __hip_atomic_fetch_add(p, v, __ATOMIC_RELAXED, __HIP_MEMORY_SCOPE_AGENT); }
; #define XB_SPIN(cond, bar) do { unsigned _sp = 0; while (cond) { __builtin_amdgcn_s_sleep(1); \
;     if ((++_sp & 255u) == 0u) { if (xb_ld(&(bar)[XB_TMO])) break; if (_sp > XB_SPIN_CAP) { atomicAdd(&(bar)[XB_TMO], 1u); break; } } } } while (0)
; DI void xcd_barrier(const XcdBarrier& b) {
;     ...
;     const unsigned old = xb_add(&bar[XB_XSUB(b.x)], 1u);
;     const unsigned gen = old / nloc;
;     if (old + 1u == (gen + 1u) * nloc) {
;       __builtin_amdgcn_fence(__ATOMIC_RELEASE, "agent");
;       asm volatile("s_waitcnt vmcnt(0)" ::: "memory");
;       const unsigned og = xb_add(&bar[XB_TOP], 1u);
;       const unsigned tg = og / nx;
;       if (og + 1u == (tg + 1u) * nx) xb_add(&bar[XB_TOPGEN], 1u);
;       else XB_SPIN(xb_ld(&bar[XB_TOPGEN]) == tg, bar);
;       __builtin_amdgcn_fence(__ATOMIC_ACQUIRE, "agent");
;       xb_add(&bar[XB_XGEN(b.x)], 1u);
;       asm volatile("s_waitcnt vmcnt(0)" ::: "memory");
;     } else {
;       XB_SPIN(xb_ld(&bar[XB_XGEN(b.x)]) == gen, bar);
.LBB0_442:
	s_or_b64 exec, exec, s[30:31]
	v_cvt_f32_u32_e32 v4, v2
	s_waitcnt vmcnt(0)
	v_readfirstlane_b32 s4, v3
	v_sub_u32_e32 v3, 0, v2
	v_rcp_iflag_f32_e32 v4, v4
	v_add_u32_e32 v5, s4, v1
	v_mul_f32_e32 v4, 0x4f7ffffe, v4
	v_cvt_u32_f32_e32 v4, v4
	v_mul_lo_u32 v1, v3, v4
	v_mul_hi_u32 v1, v4, v1
	v_add_u32_e32 v1, v4, v1
	v_mul_hi_u32 v1, v5, v1
	v_mul_lo_u32 v3, v1, v2
	v_sub_u32_e32 v3, v5, v3
	v_add_u32_e32 v4, 1, v1
	v_cmp_ge_u32_e32 vcc, v3, v2
	s_nop 1
	v_cndmask_b32_e32 v1, v1, v4, vcc
	v_sub_u32_e32 v4, v3, v2
	v_cndmask_b32_e32 v3, v3, v4, vcc
	v_add_u32_e32 v4, 1, v1
	v_cmp_ge_u32_e32 vcc, v3, v2
	v_add_u32_e32 v3, 1, v5
	s_nop 0
	v_cndmask_b32_e32 v1, v1, v4, vcc
	v_mul_lo_u32 v4, v2, v1
	v_add_u32_e32 v2, v4, v2
	v_cmp_ne_u32_e32 vcc, v3, v2
	s_and_saveexec_b64 s[4:5], vcc
	s_xor_b64 s[28:29], exec, s[4:5]
	s_cbranch_execz .LBB0_456
	s_waitcnt lgkmcnt(0)
	v_add_u32_e32 v1, 1, v1
	s_add_u32 s40, s22, 0x1c103400
	s_addc_u32 s41, s23, 0
	v_mul_lo_u32 v1, v1, v0
	v_mov_b32_e32 v0, 0
	global_load_dword v0, v0, s[40:41] sc1
	s_waitcnt vmcnt(0)
	v_cmp_lt_u32_e32 vcc, v0, v1
	s_and_saveexec_b64 s[30:31], vcc
	s_cbranch_execz .LBB0_455
	s_add_u32 s34, s22, 0x1c100200
	s_addc_u32 s35, s23, 0
	s_mov_b32 s4, 1
	s_mov_b64 s[42:43], 0
	v_mov_b32_e32 v0, 0
	s_branch .LBB0_446

; DI unsigned xb_ld(unsigned* p)              { return __hip_atomic_load(p, __ATOMIC_RELAXED, __HIP_MEMORY_SCOPE_AGENT); }
; #define XB_SPIN(cond, bar) do { unsigned _sp = 0; while (cond) { __builtin_amdgcn_s_sleep(1); \
;     if ((++_sp & 255u) == 0u) { if (xb_ld(&(bar)[XB_TMO])) break; if (_sp > XB_SPIN_CAP) { atomicAdd(&(bar)[XB_TMO], 1u); break; } } } } while (0)
; DI void xcd_barrier(const XcdBarrier& b) {
;     ...
;       XB_SPIN(xb_ld(&bar[XB_XGEN(b.x)]) == gen, bar);
.LBB0_450:
	global_load_dword v2, v0, s[40:41] sc1
	s_add_i32 s4, s4, 1
	s_mov_b64 s[48:49], -1
	s_waitcnt vmcnt(0)
	v_cmp_ge_u32_e32 vcc, v2, v1
	s_orn2_b64 s[46:47], vcc, exec
	s_branch .LBB0_445

; DI unsigned xb_ld(unsigned* p)              { return __hip_atomic_load(p, __ATOMIC_RELAXED, __HIP_MEMORY_SCOPE_AGENT); }
; DI unsigned xb_add(unsigned* p, unsigned v) { return __hip_atomic_fetch_add(p, v, __ATOMIC_RELAXED, __HIP_MEMORY_SCOPE_AGENT); }
; #define XB_SPIN(cond, bar) do { unsigned _sp = 0; while (cond) { __builtin_amdgcn_s_sleep(1); \
;     if ((++_sp & 255u) == 0u) { if (xb_ld(&(bar)[XB_TMO])) break; if (_sp > XB_SPIN_CAP) { atomicAdd(&(bar)[XB_TMO], 1u); break; } } } } while (0)
; DI void xcd_barrier(const XcdBarrier& b) {
;     ...
;       const unsigned og = xb_add(&bar[XB_TOP], 1u);
;       const unsigned tg = og / nx;
;       if (og + 1u == (tg + 1u) * nx) xb_add(&bar[XB_TOPGEN], 1u);
;       else XB_SPIN(xb_ld(&bar[XB_TOPGEN]) == tg, bar);
.LBB0_459:
	s_or_b64 exec, exec, s[30:31]
	v_cvt_f32_u32_e32 v3, v0
	s_waitcnt vmcnt(0)
	v_readfirstlane_b32 s4, v2
	s_add_u32 s30, s22, 0x1c103500
	s_addc_u32 s31, s23, 0
	v_rcp_iflag_f32_e32 v3, v3
	v_add_u32_e32 v1, s4, v1
	v_add_u32_e32 v4, 1, v1
	s_mov_b64 s[34:35], 0
	v_mul_f32_e32 v2, 0x4f7ffffe, v3
	v_cvt_u32_f32_e32 v2, v2
	v_sub_u32_e32 v3, 0, v0
	v_mul_lo_u32 v3, v3, v2
	v_mul_hi_u32 v3, v2, v3
	v_add_u32_e32 v2, v2, v3
	v_mul_hi_u32 v2, v1, v2
	v_mul_lo_u32 v3, v2, v0
	v_sub_u32_e32 v1, v1, v3
	v_add_u32_e32 v5, 1, v2
	v_cmp_ge_u32_e32 vcc, v1, v0
	v_sub_u32_e32 v3, v1, v0
	s_nop 0
	v_cndmask_b32_e32 v2, v2, v5, vcc
	v_cndmask_b32_e32 v1, v1, v3, vcc
	v_add_u32_e32 v3, 1, v2
	v_cmp_ge_u32_e32 vcc, v1, v0
	s_nop 1
	v_cndmask_b32_e32 v2, v2, v3, vcc
	v_mul_lo_u32 v1, v0, v2
	v_add_u32_e32 v0, v1, v0
	v_cmp_ne_u32_e32 vcc, v4, v0
	v_mov_b32_e32 v2, v0
	v_mov_b64_e32 v[0:1], s[30:31]
	s_and_saveexec_b64 s[28:29], vcc
	s_cbranch_execz .LBB0_471
	v_mov_b32_e32 v0, 0
	global_load_dword v1, v0, s[30:31] offset:-256 sc1
	s_mov_b64 s[42:43], 0
	s_waitcnt vmcnt(0)
	v_cmp_lt_u32_e32 vcc, v1, v2
	s_and_saveexec_b64 s[40:41], vcc
	s_cbranch_execz .LBB0_470
	s_add_u32 s34, s22, 0x1c100200
	s_addc_u32 s35, s23, 0
	s_mov_b32 s4, 1
	s_branch .LBB0_463

; DI unsigned xb_ld(unsigned* p)              { return __hip_atomic_load(p, __ATOMIC_RELAXED, __HIP_MEMORY_SCOPE_AGENT); }
; #define XB_SPIN(cond, bar) do { unsigned _sp = 0; while (cond) { __builtin_amdgcn_s_sleep(1); \
;     if ((++_sp & 255u) == 0u) { if (xb_ld(&(bar)[XB_TMO])) break; if (_sp > XB_SPIN_CAP) { atomicAdd(&(bar)[XB_TMO], 1u); break; } } } } while (0)
; DI void xcd_barrier(const XcdBarrier& b) {
;     ...
;       else XB_SPIN(xb_ld(&bar[XB_TOPGEN]) == tg, bar);
.LBB0_467:
	global_load_dword v1, v0, s[30:31] offset:-256 sc1
	s_add_i32 s4, s4, 1
	s_mov_b64 s[46:47], -1
	s_waitcnt vmcnt(0)
	v_cmp_ge_u32_e32 vcc, v1, v2
	s_orn2_b64 s[50:51], vcc, exec
	s_branch .LBB0_462

; DI unsigned xb_ld(unsigned* p)              { return __hip_atomic_load(p, __ATOMIC_RELAXED, __HIP_MEMORY_SCOPE_AGENT); }
; DI unsigned xb_add(unsigned* p, unsigned v) { return __hip_atomic_fetch_add(p, v, __ATOMIC_RELAXED, __HIP_MEMORY_SCOPE_AGENT); }
; #define XB_SPIN(cond, bar) do { unsigned _sp = 0; while (cond) { __builtin_amdgcn_s_sleep(1); \
;     if ((++_sp & 255u) == 0u) { if (xb_ld(&(bar)[XB_TMO])) break; if (_sp > XB_SPIN_CAP) { atomicAdd(&(bar)[XB_TMO], 1u); break; } } } } while (0)
; DI void xcd_barrier(const XcdBarrier& b) {
;     ...
;     const unsigned old = xb_add(&bar[XB_XSUB(b.x)], 1u);
;     const unsigned gen = old / nloc;
;     if (old + 1u == (gen + 1u) * nloc) {
;       __builtin_amdgcn_fence(__ATOMIC_RELEASE, "agent");
;       asm volatile("s_waitcnt vmcnt(0)" ::: "memory");
;       const unsigned og = xb_add(&bar[XB_TOP], 1u);
;       const unsigned tg = og / nx;
;       if (og + 1u == (tg + 1u) * nx) xb_add(&bar[XB_TOPGEN], 1u);
;       else XB_SPIN(xb_ld(&bar[XB_TOPGEN]) == tg, bar);
;       __builtin_amdgcn_fence(__ATOMIC_ACQUIRE, "agent");
;       xb_add(&bar[XB_XGEN(b.x)], 1u);
;       asm volatile("s_waitcnt vmcnt(0)" ::: "memory");
;     } else {
;       XB_SPIN(xb_ld(&bar[XB_XGEN(b.x)]) == gen, bar);
.LBB0_558:
	s_or_b64 exec, exec, s[40:41]
	v_cvt_f32_u32_e32 v4, v2
	s_waitcnt vmcnt(0)
	v_readfirstlane_b32 s4, v3
	v_sub_u32_e32 v3, 0, v2
	v_rcp_iflag_f32_e32 v4, v4
	v_add_u32_e32 v5, s4, v1
	v_mul_f32_e32 v4, 0x4f7ffffe, v4
	v_cvt_u32_f32_e32 v4, v4
	v_mul_lo_u32 v1, v3, v4
	v_mul_hi_u32 v1, v4, v1
	v_add_u32_e32 v1, v4, v1
	v_mul_hi_u32 v1, v5, v1
	v_mul_lo_u32 v3, v1, v2
	v_sub_u32_e32 v3, v5, v3
	v_add_u32_e32 v4, 1, v1
	v_cmp_ge_u32_e32 vcc, v3, v2
	s_nop 1
	v_cndmask_b32_e32 v1, v1, v4, vcc
	v_sub_u32_e32 v4, v3, v2
	v_cndmask_b32_e32 v3, v3, v4, vcc
	v_add_u32_e32 v4, 1, v1
	v_cmp_ge_u32_e32 vcc, v3, v2
	v_add_u32_e32 v3, 1, v5
	s_nop 0
	v_cndmask_b32_e32 v1, v1, v4, vcc
	v_mul_lo_u32 v4, v2, v1
	v_add_u32_e32 v2, v4, v2
	v_cmp_ne_u32_e32 vcc, v3, v2
	s_and_saveexec_b64 s[4:5], vcc
	s_xor_b64 s[28:29], exec, s[4:5]
	s_cbranch_execz .LBB0_572
	s_waitcnt lgkmcnt(0)
	v_add_u32_e32 v1, 1, v1
	s_add_u32 s44, s22, 0x1c103400
	s_addc_u32 s45, s23, 0
	v_mul_lo_u32 v1, v1, v0
	v_mov_b32_e32 v0, 0
	global_load_dword v0, v0, s[44:45] sc1
	s_waitcnt vmcnt(0)
	v_cmp_lt_u32_e32 vcc, v0, v1
	s_and_saveexec_b64 s[40:41], vcc
	s_cbranch_execz .LBB0_571
	s_add_u32 s42, s22, 0x1c100200
	s_addc_u32 s43, s23, 0
	s_mov_b32 s4, 1
	s_mov_b64 s[46:47], 0
	v_mov_b32_e32 v0, 0
	s_branch .LBB0_562

; DI unsigned xb_ld(unsigned* p)              { return __hip_atomic_load(p, __ATOMIC_RELAXED, __HIP_MEMORY_SCOPE_AGENT); }
; #define XB_SPIN(cond, bar) do { unsigned _sp = 0; while (cond) { __builtin_amdgcn_s_sleep(1); \
;     if ((++_sp & 255u) == 0u) { if (xb_ld(&(bar)[XB_TMO])) break; if (_sp > XB_SPIN_CAP) { atomicAdd(&(bar)[XB_TMO], 1u); break; } } } } while (0)
; DI void xcd_barrier(const XcdBarrier& b) {
;     ...
;       XB_SPIN(xb_ld(&bar[XB_XGEN(b.x)]) == gen, bar);
.LBB0_566:
	global_load_dword v2, v0, s[44:45] sc1
	s_add_i32 s4, s4, 1
	s_mov_b64 s[52:53], -1
	s_waitcnt vmcnt(0)
	v_cmp_ge_u32_e32 vcc, v2, v1
	s_orn2_b64 s[50:51], vcc, exec
	s_branch .LBB0_561

; DI unsigned xb_ld(unsigned* p)              { return __hip_atomic_load(p, __ATOMIC_RELAXED, __HIP_MEMORY_SCOPE_AGENT); }
; DI unsigned xb_add(unsigned* p, unsigned v) { return __hip_atomic_fetch_add(p, v, __ATOMIC_RELAXED, __HIP_MEMORY_SCOPE_AGENT); }
; #define XB_SPIN(cond, bar) do { unsigned _sp = 0; while (cond) { __builtin_amdgcn_s_sleep(1); \
;     if ((++_sp & 255u) == 0u) { if (xb_ld(&(bar)[XB_TMO])) break; if (_sp > XB_SPIN_CAP) { atomicAdd(&(bar)[XB_TMO], 1u); break; } } } } while (0)
; DI void xcd_barrier(const XcdBarrier& b) {
;     ...
;       const unsigned og = xb_add(&bar[XB_TOP], 1u);
;       const unsigned tg = og / nx;
;       if (og + 1u == (tg + 1u) * nx) xb_add(&bar[XB_TOPGEN], 1u);
;       else XB_SPIN(xb_ld(&bar[XB_TOPGEN]) == tg, bar);
.LBB0_575:
	s_or_b64 exec, exec, s[40:41]
	v_cvt_f32_u32_e32 v3, v0
	s_waitcnt vmcnt(0)
	v_readfirstlane_b32 s4, v2
	s_add_u32 s40, s22, 0x1c103500
	s_addc_u32 s41, s23, 0
	v_rcp_iflag_f32_e32 v3, v3
	v_add_u32_e32 v1, s4, v1
	v_add_u32_e32 v4, 1, v1
	s_mov_b64 s[42:43], 0
	v_mul_f32_e32 v2, 0x4f7ffffe, v3
	v_cvt_u32_f32_e32 v2, v2
	v_sub_u32_e32 v3, 0, v0
	v_mul_lo_u32 v3, v3, v2
	v_mul_hi_u32 v3, v2, v3
	v_add_u32_e32 v2, v2, v3
	v_mul_hi_u32 v2, v1, v2
	v_mul_lo_u32 v3, v2, v0
	v_sub_u32_e32 v1, v1, v3
	v_add_u32_e32 v5, 1, v2
	v_cmp_ge_u32_e32 vcc, v1, v0
	v_sub_u32_e32 v3, v1, v0
	s_nop 0
	v_cndmask_b32_e32 v2, v2, v5, vcc
	v_cndmask_b32_e32 v1, v1, v3, vcc
	v_add_u32_e32 v3, 1, v2
	v_cmp_ge_u32_e32 vcc, v1, v0
	s_nop 1
	v_cndmask_b32_e32 v2, v2, v3, vcc
	v_mul_lo_u32 v1, v0, v2
	v_add_u32_e32 v0, v1, v0
	v_cmp_ne_u32_e32 vcc, v4, v0
	v_mov_b32_e32 v2, v0
	v_mov_b64_e32 v[0:1], s[40:41]
	s_and_saveexec_b64 s[28:29], vcc
	s_cbranch_execz .LBB0_587
	v_mov_b32_e32 v0, 0
	global_load_dword v1, v0, s[40:41] offset:-256 sc1
	s_mov_b64 s[46:47], 0
	s_waitcnt vmcnt(0)
	v_cmp_lt_u32_e32 vcc, v1, v2
	s_and_saveexec_b64 s[44:45], vcc
	s_cbranch_execz .LBB0_586
	s_add_u32 s42, s22, 0x1c100200
	s_addc_u32 s43, s23, 0
	s_mov_b32 s4, 1
	s_branch .LBB0_579

; DI unsigned xb_ld(unsigned* p)              { return __hip_atomic_load(p, __ATOMIC_RELAXED, __HIP_MEMORY_SCOPE_AGENT); }
; #define XB_SPIN(cond, bar) do { unsigned _sp = 0; while (cond) { __builtin_amdgcn_s_sleep(1); \
;     if ((++_sp & 255u) == 0u) { if (xb_ld(&(bar)[XB_TMO])) break; if (_sp > XB_SPIN_CAP) { atomicAdd(&(bar)[XB_TMO], 1u); break; } } } } while (0)
; DI void xcd_barrier(const XcdBarrier& b) {
;     ...
;       else XB_SPIN(xb_ld(&bar[XB_TOPGEN]) == tg, bar);
.LBB0_583:
	global_load_dword v1, v0, s[40:41] offset:-256 sc1
	s_add_i32 s4, s4, 1
	s_mov_b64 s[50:51], -1
	s_waitcnt vmcnt(0)
	v_cmp_ge_u32_e32 vcc, v1, v2
	s_orn2_b64 s[54:55], vcc, exec
	s_branch .LBB0_578

; DI unsigned xb_ld(unsigned* p)              { return __hip_atomic_load(p, __ATOMIC_RELAXED, __HIP_MEMORY_SCOPE_AGENT); }
; DI unsigned xb_add(unsigned* p, unsigned v) { return __hip_atomic_fetch_add(p, v, __ATOMIC_RELAXED, __HIP_MEMORY_SCOPE_AGENT); }
; #define XB_SPIN(cond, bar) do { unsigned _sp = 0; while (cond) { __builtin_amdgcn_s_sleep(1); \
;     if ((++_sp & 255u) == 0u) { if (xb_ld(&(bar)[XB_TMO])) break; if (_sp > XB_SPIN_CAP) { atomicAdd(&(bar)[XB_TMO], 1u); break; } } } } while (0)
; DI void xcd_barrier(const XcdBarrier& b) {
;     ...
;     const unsigned old = xb_add(&bar[XB_XSUB(b.x)], 1u);
;     const unsigned gen = old / nloc;
;     if (old + 1u == (gen + 1u) * nloc) {
;       __builtin_amdgcn_fence(__ATOMIC_RELEASE, "agent");
;       asm volatile("s_waitcnt vmcnt(0)" ::: "memory");
;       const unsigned og = xb_add(&bar[XB_TOP], 1u);
;       const unsigned tg = og / nx;
;       if (og + 1u == (tg + 1u) * nx) xb_add(&bar[XB_TOPGEN], 1u);
;       else XB_SPIN(xb_ld(&bar[XB_TOPGEN]) == tg, bar);
;       __builtin_amdgcn_fence(__ATOMIC_ACQUIRE, "agent");
;       xb_add(&bar[XB_XGEN(b.x)], 1u);
;       asm volatile("s_waitcnt vmcnt(0)" ::: "memory");
;     } else {
;       XB_SPIN(xb_ld(&bar[XB_XGEN(b.x)]) == gen, bar);
.LBB0_640:
	s_or_b64 exec, exec, s[14:15]
	v_cvt_f32_u32_e32 v4, v2
	s_waitcnt vmcnt(0)
	v_readfirstlane_b32 s4, v3
	v_sub_u32_e32 v3, 0, v2
	v_rcp_iflag_f32_e32 v4, v4
	v_add_u32_e32 v5, s4, v1
	v_mul_f32_e32 v4, 0x4f7ffffe, v4
	v_cvt_u32_f32_e32 v4, v4
	v_mul_lo_u32 v1, v3, v4
	v_mul_hi_u32 v1, v4, v1
	v_add_u32_e32 v1, v4, v1
	v_mul_hi_u32 v1, v5, v1
	v_mul_lo_u32 v3, v1, v2
	v_sub_u32_e32 v3, v5, v3
	v_add_u32_e32 v4, 1, v1
	v_cmp_ge_u32_e32 vcc, v3, v2
	s_nop 1
	v_cndmask_b32_e32 v1, v1, v4, vcc
	v_sub_u32_e32 v4, v3, v2
	v_cndmask_b32_e32 v3, v3, v4, vcc
	v_add_u32_e32 v4, 1, v1
	v_cmp_ge_u32_e32 vcc, v3, v2
	v_add_u32_e32 v3, 1, v5
	s_nop 0
	v_cndmask_b32_e32 v1, v1, v4, vcc
	v_mul_lo_u32 v4, v2, v1
	v_add_u32_e32 v2, v4, v2
	v_cmp_ne_u32_e32 vcc, v3, v2
	s_and_saveexec_b64 s[4:5], vcc
	s_xor_b64 s[12:13], exec, s[4:5]
	s_cbranch_execz .LBB0_654
	s_waitcnt lgkmcnt(0)
	v_add_u32_e32 v1, 1, v1
	s_add_u32 s18, s22, 0x1c103400
	s_addc_u32 s19, s23, 0
	v_mul_lo_u32 v1, v1, v0
	v_mov_b32_e32 v0, 0
	global_load_dword v0, v0, s[18:19] sc1
	s_waitcnt vmcnt(0)
	v_cmp_lt_u32_e32 vcc, v0, v1
	s_and_saveexec_b64 s[14:15], vcc
	s_cbranch_execz .LBB0_653
	s_add_u32 s16, s22, 0x1c100200
	s_addc_u32 s17, s23, 0
	s_mov_b32 s4, 1
	s_mov_b64 s[28:29], 0
	v_mov_b32_e32 v0, 0
	s_branch .LBB0_644

; DI unsigned xb_ld(unsigned* p)              { return __hip_atomic_load(p, __ATOMIC_RELAXED, __HIP_MEMORY_SCOPE_AGENT); }
; #define XB_SPIN(cond, bar) do { unsigned _sp = 0; while (cond) { __builtin_amdgcn_s_sleep(1); \
;     if ((++_sp & 255u) == 0u) { if (xb_ld(&(bar)[XB_TMO])) break; if (_sp > XB_SPIN_CAP) { atomicAdd(&(bar)[XB_TMO], 1u); break; } } } } while (0)
; DI void xcd_barrier(const XcdBarrier& b) {
;     ...
;       XB_SPIN(xb_ld(&bar[XB_XGEN(b.x)]) == gen, bar);
.LBB0_648:
	global_load_dword v2, v0, s[18:19] sc1
	s_add_i32 s4, s4, 1
	s_mov_b64 s[42:43], -1
	s_waitcnt vmcnt(0)
	v_cmp_ge_u32_e32 vcc, v2, v1
	s_orn2_b64 s[40:41], vcc, exec
	s_branch .LBB0_643

; DI unsigned xb_ld(unsigned* p)              { return __hip_atomic_load(p, __ATOMIC_RELAXED, __HIP_MEMORY_SCOPE_AGENT); }
; DI unsigned xb_add(unsigned* p, unsigned v) { return __hip_atomic_fetch_add(p, v, __ATOMIC_RELAXED, __HIP_MEMORY_SCOPE_AGENT); }
; #define XB_SPIN(cond, bar) do { unsigned _sp = 0; while (cond) { __builtin_amdgcn_s_sleep(1); \
;     if ((++_sp & 255u) == 0u) { if (xb_ld(&(bar)[XB_TMO])) break; if (_sp > XB_SPIN_CAP) { atomicAdd(&(bar)[XB_TMO], 1u); break; } } } } while (0)
; DI void xcd_barrier(const XcdBarrier& b) {
;     ...
;       const unsigned og = xb_add(&bar[XB_TOP], 1u);
;       const unsigned tg = og / nx;
;       if (og + 1u == (tg + 1u) * nx) xb_add(&bar[XB_TOPGEN], 1u);
;       else XB_SPIN(xb_ld(&bar[XB_TOPGEN]) == tg, bar);
.LBB0_657:
	s_or_b64 exec, exec, s[14:15]
	v_cvt_f32_u32_e32 v3, v0
	s_waitcnt vmcnt(0)
	v_readfirstlane_b32 s4, v2
	s_add_u32 s14, s22, 0x1c103500
	s_addc_u32 s15, s23, 0
	v_rcp_iflag_f32_e32 v3, v3
	v_add_u32_e32 v1, s4, v1
	v_add_u32_e32 v4, 1, v1
	s_mov_b64 s[16:17], 0
	v_mul_f32_e32 v2, 0x4f7ffffe, v3
	v_cvt_u32_f32_e32 v2, v2
	v_sub_u32_e32 v3, 0, v0
	v_mul_lo_u32 v3, v3, v2
	v_mul_hi_u32 v3, v2, v3
	v_add_u32_e32 v2, v2, v3
	v_mul_hi_u32 v2, v1, v2
	v_mul_lo_u32 v3, v2, v0
	v_sub_u32_e32 v1, v1, v3
	v_add_u32_e32 v5, 1, v2
	v_cmp_ge_u32_e32 vcc, v1, v0
	v_sub_u32_e32 v3, v1, v0
	s_nop 0
	v_cndmask_b32_e32 v2, v2, v5, vcc
	v_cndmask_b32_e32 v1, v1, v3, vcc
	v_add_u32_e32 v3, 1, v2
	v_cmp_ge_u32_e32 vcc, v1, v0
	s_nop 1
	v_cndmask_b32_e32 v2, v2, v3, vcc
	v_mul_lo_u32 v1, v0, v2
	v_add_u32_e32 v0, v1, v0
	v_cmp_ne_u32_e32 vcc, v4, v0
	v_mov_b32_e32 v2, v0
	v_mov_b64_e32 v[0:1], s[14:15]
	s_and_saveexec_b64 s[12:13], vcc
	s_cbranch_execz .LBB0_669
	v_mov_b32_e32 v0, 0
	global_load_dword v1, v0, s[14:15] offset:-256 sc1
	s_mov_b64 s[28:29], 0
	s_waitcnt vmcnt(0)
	v_cmp_lt_u32_e32 vcc, v1, v2
	s_and_saveexec_b64 s[18:19], vcc
	s_cbranch_execz .LBB0_668
	s_add_u32 s16, s22, 0x1c100200
	s_addc_u32 s17, s23, 0
	s_mov_b32 s4, 1
	s_branch .LBB0_661

; DI unsigned xb_ld(unsigned* p)              { return __hip_atomic_load(p, __ATOMIC_RELAXED, __HIP_MEMORY_SCOPE_AGENT); }
; DI unsigned xb_add(unsigned* p, unsigned v) { return __hip_atomic_fetch_add(p, v, __ATOMIC_RELAXED, __HIP_MEMORY_SCOPE_AGENT); }
; #define XB_SPIN(cond, bar) do { unsigned _sp = 0; while (cond) { __builtin_amdgcn_s_sleep(1); \
;     if ((++_sp & 255u) == 0u) { if (xb_ld(&(bar)[XB_TMO])) break; if (_sp > XB_SPIN_CAP) { atomicAdd(&(bar)[XB_TMO], 1u); break; } } } } while (0)
; DI void xcd_barrier(const XcdBarrier& b) {
;     ...
;       const unsigned og = xb_add(&bar[XB_TOP], 1u);
;       const unsigned tg = og / nx;
;       if (og + 1u == (tg + 1u) * nx) xb_add(&bar[XB_TOPGEN], 1u);
;       else XB_SPIN(xb_ld(&bar[XB_TOPGEN]) == tg, bar);
.LBB0_665:
	global_load_dword v1, v0, s[14:15] offset:-256 sc1
	s_add_i32 s4, s4, 1
	s_mov_b64 s[40:41], -1
	s_waitcnt vmcnt(0)
	v_cmp_ge_u32_e32 vcc, v1, v2
	s_orn2_b64 s[44:45], vcc, exec
	s_branch .LBB0_660

; DI unsigned xb_ld(unsigned* p)              { return __hip_atomic_load(p, __ATOMIC_RELAXED, __HIP_MEMORY_SCOPE_AGENT); }
; #define XB_SPIN(cond, bar) do { unsigned _sp = 0; while (cond) { __builtin_amdgcn_s_sleep(1); \
;     if ((++_sp & 255u) == 0u) { if (xb_ld(&(bar)[XB_TMO])) break; if (_sp > XB_SPIN_CAP) { atomicAdd(&(bar)[XB_TMO], 1u); break; } } } } while (0)
; DI void xcd_barrier(const XcdBarrier& b) {
;     ...
;     } else {
;       XB_SPIN(xb_ld(&bar[XB_XGEN(b.x)]) == gen, bar);
.LBB0_910:
	global_load_dword v2, v0, s[18:19] sc1
	s_add_i32 s4, s4, 1
	s_mov_b64 s[44:45], -1
	s_waitcnt vmcnt(0)
	v_cmp_ge_u32_e32 vcc, v2, v1
	s_orn2_b64 s[42:43], vcc, exec
	s_branch .LBB0_905

; DI unsigned xb_ld(unsigned* p)              { return __hip_atomic_load(p, __ATOMIC_RELAXED, __HIP_MEMORY_SCOPE_AGENT); }
; DI unsigned xb_add(unsigned* p, unsigned v) { return __hip_atomic_fetch_add(p, v, __ATOMIC_RELAXED, __HIP_MEMORY_SCOPE_AGENT); }
; #define XB_SPIN(cond, bar) do { unsigned _sp = 0; while (cond) { __builtin_amdgcn_s_sleep(1); \
;     if ((++_sp & 255u) == 0u) { if (xb_ld(&(bar)[XB_TMO])) break; if (_sp > XB_SPIN_CAP) { atomicAdd(&(bar)[XB_TMO], 1u); break; } } } } while (0)
; DI void xcd_barrier(const XcdBarrier& b) {
;     ...
;       const unsigned og = xb_add(&bar[XB_TOP], 1u);
;       const unsigned tg = og / nx;
;       if (og + 1u == (tg + 1u) * nx) xb_add(&bar[XB_TOPGEN], 1u);
;       else XB_SPIN(xb_ld(&bar[XB_TOPGEN]) == tg, bar);
.LBB0_927:
	global_load_dword v1, v0, s[14:15] offset:-256 sc1
	s_add_i32 s4, s4, 1
	s_mov_b64 s[42:43], -1
	s_waitcnt vmcnt(0)
	v_cmp_ge_u32_e32 vcc, v1, v2
	s_orn2_b64 s[46:47], vcc, exec
	s_branch .LBB0_922

; DI unsigned xb_ld(unsigned* p)              { return __hip_atomic_load(p, __ATOMIC_RELAXED, __HIP_MEMORY_SCOPE_AGENT); }
; DI unsigned xb_add(unsigned* p, unsigned v) { return __hip_atomic_fetch_add(p, v, __ATOMIC_RELAXED, __HIP_MEMORY_SCOPE_AGENT); }
; #define XB_SPIN(cond, bar) do { unsigned _sp = 0; while (cond) { __builtin_amdgcn_s_sleep(1); \
;     if ((++_sp & 255u) == 0u) { if (xb_ld(&(bar)[XB_TMO])) break; if (_sp > XB_SPIN_CAP) { atomicAdd(&(bar)[XB_TMO], 1u); break; } } } } while (0)
; DI void xcd_barrier(const XcdBarrier& b) {
;     ...
;     unsigned nloc = b.st[0], nx = b.st[1];
;     if (nloc == 0u) { xcd_barrier_complete(bar, b.x, nloc, nx); b.st[0] = nloc; b.st[1] = nx; }
;     const unsigned old = xb_add(&bar[XB_XSUB(b.x)], 1u);
;     const unsigned gen = old / nloc;
;     if (old + 1u == (gen + 1u) * nloc) {
;       __builtin_amdgcn_fence(__ATOMIC_RELEASE, "agent");
;       asm volatile("s_waitcnt vmcnt(0)" ::: "memory");
;       const unsigned og = xb_add(&bar[XB_TOP], 1u);
;       const unsigned tg = og / nx;
;       if (og + 1u == (tg + 1u) * nx) xb_add(&bar[XB_TOPGEN], 1u);
;       else XB_SPIN(xb_ld(&bar[XB_TOPGEN]) == tg, bar);
;       __builtin_amdgcn_fence(__ATOMIC_ACQUIRE, "agent");
;       xb_add(&bar[XB_XGEN(b.x)], 1u);
;       asm volatile("s_waitcnt vmcnt(0)" ::: "memory");
;     } else {
;       XB_SPIN(xb_ld(&bar[XB_XGEN(b.x)]) == gen, bar);
.LBB0_1221:
	s_or_b64 exec, exec, s[14:15]
	v_cvt_f32_u32_e32 v4, v2
	s_waitcnt vmcnt(0)
	v_readfirstlane_b32 s0, v3
	v_sub_u32_e32 v3, 0, v2
	v_rcp_iflag_f32_e32 v4, v4
	v_add_u32_e32 v5, s0, v1
	v_mul_f32_e32 v4, 0x4f7ffffe, v4
	v_cvt_u32_f32_e32 v4, v4
	v_mul_lo_u32 v1, v3, v4
	v_mul_hi_u32 v1, v4, v1
	v_add_u32_e32 v1, v4, v1
	v_mul_hi_u32 v1, v5, v1
	v_mul_lo_u32 v3, v1, v2
	v_sub_u32_e32 v3, v5, v3
	v_add_u32_e32 v4, 1, v1
	v_cmp_ge_u32_e32 vcc, v3, v2
	s_nop 1
	v_cndmask_b32_e32 v1, v1, v4, vcc
	v_sub_u32_e32 v4, v3, v2
	v_cndmask_b32_e32 v3, v3, v4, vcc
	v_add_u32_e32 v4, 1, v1
	v_cmp_ge_u32_e32 vcc, v3, v2
	v_add_u32_e32 v3, 1, v5
	s_nop 0
	v_cndmask_b32_e32 v1, v1, v4, vcc
	v_mul_lo_u32 v4, v2, v1
	v_add_u32_e32 v2, v4, v2
	v_cmp_ne_u32_e32 vcc, v3, v2
	s_and_saveexec_b64 s[4:5], vcc
	s_xor_b64 s[12:13], exec, s[4:5]
	s_cbranch_execz .LBB0_1235
	s_waitcnt lgkmcnt(0)
	v_add_u32_e32 v1, 1, v1
	s_add_u32 s18, s22, 0x1c103400
	s_addc_u32 s19, s23, 0
	v_mul_lo_u32 v1, v1, v0
	v_mov_b32_e32 v0, 0
	global_load_dword v0, v0, s[18:19] sc1
	s_waitcnt vmcnt(0)
	v_cmp_lt_u32_e32 vcc, v0, v1
	s_and_saveexec_b64 s[14:15], vcc
	s_cbranch_execz .LBB0_1234
	s_add_u32 s16, s22, 0x1c100200
	s_addc_u32 s17, s23, 0
	s_mov_b32 s4, 1
	s_mov_b64 s[20:21], 0
	v_mov_b32_e32 v0, 0
	s_branch .LBB0_1225

; DI unsigned xb_ld(unsigned* p)              { return __hip_atomic_load(p, __ATOMIC_RELAXED, __HIP_MEMORY_SCOPE_AGENT); }
; DI unsigned xb_add(unsigned* p, unsigned v) { return __hip_atomic_fetch_add(p, v, __ATOMIC_RELAXED, __HIP_MEMORY_SCOPE_AGENT); }
; #define XB_SPIN(cond, bar) do { unsigned _sp = 0; while (cond) { __builtin_amdgcn_s_sleep(1); \
;     if ((++_sp & 255u) == 0u) { if (xb_ld(&(bar)[XB_TMO])) break; if (_sp > XB_SPIN_CAP) { atomicAdd(&(bar)[XB_TMO], 1u); break; } } } } while (0)
; DI void xcd_barrier(const XcdBarrier& b) {
;     ...
;       __builtin_amdgcn_fence(__ATOMIC_RELEASE, "agent");
;       asm volatile("s_waitcnt vmcnt(0)" ::: "memory");
;       const unsigned og = xb_add(&bar[XB_TOP], 1u);
;       const unsigned tg = og / nx;
;       if (og + 1u == (tg + 1u) * nx) xb_add(&bar[XB_TOPGEN], 1u);
;       else XB_SPIN(xb_ld(&bar[XB_TOPGEN]) == tg, bar);
.LBB0_1238:
	s_or_b64 exec, exec, s[14:15]
	v_cvt_f32_u32_e32 v3, v0
	s_waitcnt vmcnt(0)
	v_readfirstlane_b32 s0, v2
	s_add_u32 s14, s22, 0x1c103500
	s_addc_u32 s15, s23, 0
	v_rcp_iflag_f32_e32 v3, v3
	v_add_u32_e32 v1, s0, v1
	v_add_u32_e32 v4, 1, v1
	s_mov_b64 s[16:17], 0
	v_mul_f32_e32 v2, 0x4f7ffffe, v3
	v_cvt_u32_f32_e32 v2, v2
	v_sub_u32_e32 v3, 0, v0
	v_mul_lo_u32 v3, v3, v2
	v_mul_hi_u32 v3, v2, v3
	v_add_u32_e32 v2, v2, v3
	v_mul_hi_u32 v2, v1, v2
	v_mul_lo_u32 v3, v2, v0
	v_sub_u32_e32 v1, v1, v3
	v_add_u32_e32 v5, 1, v2
	v_cmp_ge_u32_e32 vcc, v1, v0
	v_sub_u32_e32 v3, v1, v0
	s_nop 0
	v_cndmask_b32_e32 v2, v2, v5, vcc
	v_cndmask_b32_e32 v1, v1, v3, vcc
	v_add_u32_e32 v3, 1, v2
	v_cmp_ge_u32_e32 vcc, v1, v0
	s_nop 1
	v_cndmask_b32_e32 v2, v2, v3, vcc
	v_mul_lo_u32 v1, v0, v2
	v_add_u32_e32 v0, v1, v0
	v_cmp_ne_u32_e32 vcc, v4, v0
	v_mov_b32_e32 v2, v0
	v_mov_b64_e32 v[0:1], s[14:15]
	s_and_saveexec_b64 s[12:13], vcc
	s_cbranch_execz .LBB0_1250
	v_mov_b32_e32 v0, 0
	global_load_dword v1, v0, s[14:15] offset:-256 sc1
	s_mov_b64 s[20:21], 0
	s_waitcnt vmcnt(0)
	v_cmp_lt_u32_e32 vcc, v1, v2
	s_and_saveexec_b64 s[18:19], vcc
	s_cbranch_execz .LBB0_1249
	s_add_u32 s16, s22, 0x1c100200
	s_addc_u32 s17, s23, 0
	s_mov_b32 s4, 1
	s_branch .LBB0_1242

; DI unsigned xb_ld(unsigned* p)              { return __hip_atomic_load(p, __ATOMIC_RELAXED, __HIP_MEMORY_SCOPE_AGENT); }
; #define XB_SPIN(cond, bar) do { unsigned _sp = 0; while (cond) { __builtin_amdgcn_s_sleep(1); \
;     if ((++_sp & 255u) == 0u) { if (xb_ld(&(bar)[XB_TMO])) break; if (_sp > XB_SPIN_CAP) { atomicAdd(&(bar)[XB_TMO], 1u); break; } } } } while (0)
; DI void xcd_barrier(const XcdBarrier& b) {
;     ...
;     } else {
;       XB_SPIN(xb_ld(&bar[XB_XGEN(b.x)]) == gen, bar);
.LBB0_1349:
	global_load_dword v2, v0, s[18:19] sc1
	s_add_i32 s4, s4, 1
	s_mov_b64 s[40:41], -1
	s_waitcnt vmcnt(0)
	v_cmp_ge_u32_e32 vcc, v2, v1
	s_orn2_b64 s[36:37], vcc, exec
	s_branch .LBB0_1344

; DI unsigned xb_ld(unsigned* p)              { return __hip_atomic_load(p, __ATOMIC_RELAXED, __HIP_MEMORY_SCOPE_AGENT); }
; DI unsigned xb_add(unsigned* p, unsigned v) { return __hip_atomic_fetch_add(p, v, __ATOMIC_RELAXED, __HIP_MEMORY_SCOPE_AGENT); }
; #define XB_SPIN(cond, bar) do { unsigned _sp = 0; while (cond) { __builtin_amdgcn_s_sleep(1); \
;     if ((++_sp & 255u) == 0u) { if (xb_ld(&(bar)[XB_TMO])) break; if (_sp > XB_SPIN_CAP) { atomicAdd(&(bar)[XB_TMO], 1u); break; } } } } while (0)
; DI void xcd_barrier(const XcdBarrier& b) {
;     ...
;       const unsigned og = xb_add(&bar[XB_TOP], 1u);
;       const unsigned tg = og / nx;
;       if (og + 1u == (tg + 1u) * nx) xb_add(&bar[XB_TOPGEN], 1u);
;       else XB_SPIN(xb_ld(&bar[XB_TOPGEN]) == tg, bar);
.LBB0_1366:
	global_load_dword v1, v0, s[14:15] offset:-256 sc1
	s_add_i32 s4, s4, 1
	s_mov_b64 s[36:37], -1
	s_waitcnt vmcnt(0)
	v_cmp_ge_u32_e32 vcc, v1, v2
	s_orn2_b64 s[42:43], vcc, exec
	s_branch .LBB0_1361

; DI unsigned xb_ld(unsigned* p)              { return __hip_atomic_load(p, __ATOMIC_RELAXED, __HIP_MEMORY_SCOPE_AGENT); }
; #define XB_SPIN(cond, bar) do { unsigned _sp = 0; while (cond) { __builtin_amdgcn_s_sleep(1); \
;     if ((++_sp & 255u) == 0u) { if (xb_ld(&(bar)[XB_TMO])) break; if (_sp > XB_SPIN_CAP) { atomicAdd(&(bar)[XB_TMO], 1u); break; } } } } while (0)
; DI void xcd_barrier(const XcdBarrier& b) {
;     ...
;     } else {
;       XB_SPIN(xb_ld(&bar[XB_XGEN(b.x)]) == gen, bar);
.LBB0_1404:
	global_load_dword v2, v0, s[18:19] sc1
	s_add_i32 s4, s4, 1
	s_mov_b64 s[38:39], -1
	s_waitcnt vmcnt(0)
	v_cmp_ge_u32_e32 vcc, v2, v1
	s_orn2_b64 s[36:37], vcc, exec
	s_branch .LBB0_1399

; DI unsigned xb_ld(unsigned* p)              { return __hip_atomic_load(p, __ATOMIC_RELAXED, __HIP_MEMORY_SCOPE_AGENT); }
; DI unsigned xb_add(unsigned* p, unsigned v) { return __hip_atomic_fetch_add(p, v, __ATOMIC_RELAXED, __HIP_MEMORY_SCOPE_AGENT); }
; #define XB_SPIN(cond, bar) do { unsigned _sp = 0; while (cond) { __builtin_amdgcn_s_sleep(1); \
;     if ((++_sp & 255u) == 0u) { if (xb_ld(&(bar)[XB_TMO])) break; if (_sp > XB_SPIN_CAP) { atomicAdd(&(bar)[XB_TMO], 1u); break; } } } } while (0)
; DI void xcd_barrier(const XcdBarrier& b) {
;     ...
;       const unsigned og = xb_add(&bar[XB_TOP], 1u);
;       const unsigned tg = og / nx;
;       if (og + 1u == (tg + 1u) * nx) xb_add(&bar[XB_TOPGEN], 1u);
;       else XB_SPIN(xb_ld(&bar[XB_TOPGEN]) == tg, bar);
.LBB0_1421:
	global_load_dword v1, v0, s[14:15] offset:-256 sc1
	s_add_i32 s4, s4, 1
	s_mov_b64 s[36:37], -1
	s_waitcnt vmcnt(0)
	v_cmp_ge_u32_e32 vcc, v1, v2
	s_orn2_b64 s[40:41], vcc, exec
	s_branch .LBB0_1416

; DI unsigned xb_ld(unsigned* p)              { return __hip_atomic_load(p, __ATOMIC_RELAXED, __HIP_MEMORY_SCOPE_AGENT); }
; #define XB_SPIN(cond, bar) do { unsigned _sp = 0; while (cond) { __builtin_amdgcn_s_sleep(1); \
;     if ((++_sp & 255u) == 0u) { if (xb_ld(&(bar)[XB_TMO])) break; if (_sp > XB_SPIN_CAP) { atomicAdd(&(bar)[XB_TMO], 1u); break; } } } } while (0)
; DI void xcd_barrier(const XcdBarrier& b) {
;     ...
;     } else {
;       XB_SPIN(xb_ld(&bar[XB_XGEN(b.x)]) == gen, bar);
.LBB0_1471:
	global_load_dword v2, v0, s[16:17] sc1
	s_add_i32 s0, s0, 1
	s_mov_b64 s[36:37], -1
	s_waitcnt vmcnt(0)
	v_cmp_ge_u32_e32 vcc, v2, v1
	s_orn2_b64 s[28:29], vcc, exec
	s_branch .LBB0_1466

; DI unsigned xb_ld(unsigned* p)              { return __hip_atomic_load(p, __ATOMIC_RELAXED, __HIP_MEMORY_SCOPE_AGENT); }
; DI unsigned xb_add(unsigned* p, unsigned v) { return __hip_atomic_fetch_add(p, v, __ATOMIC_RELAXED, __HIP_MEMORY_SCOPE_AGENT); }
; #define XB_SPIN(cond, bar) do { unsigned _sp = 0; while (cond) { __builtin_amdgcn_s_sleep(1); \
;     if ((++_sp & 255u) == 0u) { if (xb_ld(&(bar)[XB_TMO])) break; if (_sp > XB_SPIN_CAP) { atomicAdd(&(bar)[XB_TMO], 1u); break; } } } } while (0)
; DI void xcd_barrier(const XcdBarrier& b) {
;     ...
;       const unsigned og = xb_add(&bar[XB_TOP], 1u);
;       const unsigned tg = og / nx;
;       if (og + 1u == (tg + 1u) * nx) xb_add(&bar[XB_TOPGEN], 1u);
;       else XB_SPIN(xb_ld(&bar[XB_TOPGEN]) == tg, bar);
.LBB0_1488:
	global_load_dword v1, v0, s[12:13] offset:-256 sc1
	s_add_i32 s0, s0, 1
	s_mov_b64 s[28:29], -1
	s_waitcnt vmcnt(0)
	v_cmp_ge_u32_e32 vcc, v1, v2
	s_orn2_b64 s[38:39], vcc, exec
	s_branch .LBB0_1483

; DI unsigned xb_ld(unsigned* p)              { return __hip_atomic_load(p, __ATOMIC_RELAXED, __HIP_MEMORY_SCOPE_AGENT); }
; DI unsigned xb_add(unsigned* p, unsigned v) { return __hip_atomic_fetch_add(p, v, __ATOMIC_RELAXED, __HIP_MEMORY_SCOPE_AGENT); }
; #define XB_SPIN(cond, bar) do { unsigned _sp = 0; while (cond) { __builtin_amdgcn_s_sleep(1); \
;     if ((++_sp & 255u) == 0u) { if (xb_ld(&(bar)[XB_TMO])) break; if (_sp > XB_SPIN_CAP) { atomicAdd(&(bar)[XB_TMO], 1u); break; } } } } while (0)
; DI void xcd_barrier(const XcdBarrier& b) {
;     ...
;     unsigned nloc = b.st[0], nx = b.st[1];
;     if (nloc == 0u) { xcd_barrier_complete(bar, b.x, nloc, nx); b.st[0] = nloc; b.st[1] = nx; }
;     const unsigned old = xb_add(&bar[XB_XSUB(b.x)], 1u);
;     const unsigned gen = old / nloc;
;     if (old + 1u == (gen + 1u) * nloc) {
;       __builtin_amdgcn_fence(__ATOMIC_RELEASE, "agent");
;       asm volatile("s_waitcnt vmcnt(0)" ::: "memory");
;       const unsigned og = xb_add(&bar[XB_TOP], 1u);
;       const unsigned tg = og / nx;
;       if (og + 1u == (tg + 1u) * nx) xb_add(&bar[XB_TOPGEN], 1u);
;       else XB_SPIN(xb_ld(&bar[XB_TOPGEN]) == tg, bar);
;       __builtin_amdgcn_fence(__ATOMIC_ACQUIRE, "agent");
;       xb_add(&bar[XB_XGEN(b.x)], 1u);
;       asm volatile("s_waitcnt vmcnt(0)" ::: "memory");
;     } else {
;       XB_SPIN(xb_ld(&bar[XB_XGEN(b.x)]) == gen, bar);
.LBB0_1537:
	s_or_b64 exec, exec, s[12:13]
	v_cvt_f32_u32_e32 v4, v2
	s_waitcnt vmcnt(0)
	v_readfirstlane_b32 s0, v3
	v_sub_u32_e32 v3, 0, v2
	v_rcp_iflag_f32_e32 v4, v4
	v_add_u32_e32 v5, s0, v1
	v_mul_f32_e32 v4, 0x4f7ffffe, v4
	v_cvt_u32_f32_e32 v4, v4
	v_mul_lo_u32 v1, v3, v4
	v_mul_hi_u32 v1, v4, v1
	v_add_u32_e32 v1, v4, v1
	v_mul_hi_u32 v1, v5, v1
	v_mul_lo_u32 v3, v1, v2
	v_sub_u32_e32 v3, v5, v3
	v_add_u32_e32 v4, 1, v1
	v_cmp_ge_u32_e32 vcc, v3, v2
	s_nop 1
	v_cndmask_b32_e32 v1, v1, v4, vcc
	v_sub_u32_e32 v4, v3, v2
	v_cndmask_b32_e32 v3, v3, v4, vcc
	v_add_u32_e32 v4, 1, v1
	v_cmp_ge_u32_e32 vcc, v3, v2
	v_add_u32_e32 v3, 1, v5
	s_nop 0
	v_cndmask_b32_e32 v1, v1, v4, vcc
	v_mul_lo_u32 v4, v2, v1
	v_add_u32_e32 v2, v4, v2
	v_cmp_ne_u32_e32 vcc, v3, v2
	s_and_saveexec_b64 s[0:1], vcc
	v_readlane_b32 s2, v255, 0
	s_xor_b64 s[10:11], exec, s[0:1]
	v_readlane_b32 s3, v255, 1
	s_cbranch_execz .LBB0_1551
	s_waitcnt lgkmcnt(0)
	v_add_u32_e32 v1, 1, v1
	s_add_u32 s16, s22, 0x1c103400
	s_addc_u32 s17, s23, 0
	v_mul_lo_u32 v1, v1, v0
	v_mov_b32_e32 v0, 0
	global_load_dword v0, v0, s[16:17] sc1
	s_waitcnt vmcnt(0)
	v_cmp_lt_u32_e32 vcc, v0, v1
	s_and_saveexec_b64 s[12:13], vcc
	s_cbranch_execz .LBB0_1550
	s_add_u32 s14, s22, 0x1c100200
	s_addc_u32 s15, s23, 0
	s_mov_b32 s0, 1
	s_mov_b64 s[18:19], 0
	v_mov_b32_e32 v0, 0
	s_branch .LBB0_1541

; DI unsigned xb_ld(unsigned* p)              { return __hip_atomic_load(p, __ATOMIC_RELAXED, __HIP_MEMORY_SCOPE_AGENT); }
; DI unsigned xb_add(unsigned* p, unsigned v) { return __hip_atomic_fetch_add(p, v, __ATOMIC_RELAXED, __HIP_MEMORY_SCOPE_AGENT); }
; #define XB_SPIN(cond, bar) do { unsigned _sp = 0; while (cond) { __builtin_amdgcn_s_sleep(1); \
;     if ((++_sp & 255u) == 0u) { if (xb_ld(&(bar)[XB_TMO])) break; if (_sp > XB_SPIN_CAP) { atomicAdd(&(bar)[XB_TMO], 1u); break; } } } } while (0)
; DI void xcd_barrier(const XcdBarrier& b) {
;     ...
;     unsigned nloc = b.st[0], nx = b.st[1];
;     if (nloc == 0u) { xcd_barrier_complete(bar, b.x, nloc, nx); b.st[0] = nloc; b.st[1] = nx; }
;     const unsigned old = xb_add(&bar[XB_XSUB(b.x)], 1u);
;     const unsigned gen = old / nloc;
;     if (old + 1u == (gen + 1u) * nloc) {
;       __builtin_amdgcn_fence(__ATOMIC_RELEASE, "agent");
;       asm volatile("s_waitcnt vmcnt(0)" ::: "memory");
;       const unsigned og = xb_add(&bar[XB_TOP], 1u);
;       const unsigned tg = og / nx;
;       if (og + 1u == (tg + 1u) * nx) xb_add(&bar[XB_TOPGEN], 1u);
;       else XB_SPIN(xb_ld(&bar[XB_TOPGEN]) == tg, bar);
;       __builtin_amdgcn_fence(__ATOMIC_ACQUIRE, "agent");
;       xb_add(&bar[XB_XGEN(b.x)], 1u);
;       asm volatile("s_waitcnt vmcnt(0)" ::: "memory");
;     } else {
;       XB_SPIN(xb_ld(&bar[XB_XGEN(b.x)]) == gen, bar);
.LBB0_1596:
	s_or_b64 exec, exec, s[10:11]
	v_cvt_f32_u32_e32 v4, v2
	s_waitcnt vmcnt(0)
	v_readfirstlane_b32 s0, v3
	v_sub_u32_e32 v3, 0, v2
	v_rcp_iflag_f32_e32 v4, v4
	v_add_u32_e32 v5, s0, v1
	v_mul_f32_e32 v4, 0x4f7ffffe, v4
	v_cvt_u32_f32_e32 v4, v4
	v_mul_lo_u32 v1, v3, v4
	v_mul_hi_u32 v1, v4, v1
	v_add_u32_e32 v1, v4, v1
	v_mul_hi_u32 v1, v5, v1
	v_mul_lo_u32 v3, v1, v2
	v_sub_u32_e32 v3, v5, v3
	v_add_u32_e32 v4, 1, v1
	v_cmp_ge_u32_e32 vcc, v3, v2
	s_nop 1
	v_cndmask_b32_e32 v1, v1, v4, vcc
	v_sub_u32_e32 v4, v3, v2
	v_cndmask_b32_e32 v3, v3, v4, vcc
	v_add_u32_e32 v4, 1, v1
	v_cmp_ge_u32_e32 vcc, v3, v2
	v_add_u32_e32 v3, 1, v5
	s_nop 0
	v_cndmask_b32_e32 v1, v1, v4, vcc
	v_mul_lo_u32 v4, v2, v1
	v_add_u32_e32 v2, v4, v2
	v_cmp_ne_u32_e32 vcc, v3, v2
	s_and_saveexec_b64 s[0:1], vcc
	s_xor_b64 s[8:9], exec, s[0:1]
	s_cbranch_execz .LBB0_1610
	s_waitcnt lgkmcnt(0)
	v_add_u32_e32 v1, 1, v1
	s_add_u32 s14, s22, 0x1c103400
	s_addc_u32 s15, s23, 0
	v_mul_lo_u32 v1, v1, v0
	v_mov_b32_e32 v0, 0
	global_load_dword v0, v0, s[14:15] sc1
	s_waitcnt vmcnt(0)
	v_cmp_lt_u32_e32 vcc, v0, v1
	s_and_saveexec_b64 s[10:11], vcc
	s_cbranch_execz .LBB0_1609
	s_add_u32 s12, s22, 0x1c100200
	s_addc_u32 s13, s23, 0
	s_mov_b32 s0, 1
	s_mov_b64 s[16:17], 0
	v_mov_b32_e32 v0, 0
	s_branch .LBB0_1600

; DI unsigned xb_ld(unsigned* p)              { return __hip_atomic_load(p, __ATOMIC_RELAXED, __HIP_MEMORY_SCOPE_AGENT); }
; #define XB_SPIN(cond, bar) do { unsigned _sp = 0; while (cond) { __builtin_amdgcn_s_sleep(1); \
;     if ((++_sp & 255u) == 0u) { if (xb_ld(&(bar)[XB_TMO])) break; if (_sp > XB_SPIN_CAP) { atomicAdd(&(bar)[XB_TMO], 1u); break; } } } } while (0)
; DI void xcd_barrier(const XcdBarrier& b) {
;     ...
;     } else {
;       XB_SPIN(xb_ld(&bar[XB_XGEN(b.x)]) == gen, bar);
.LBB0_1604:
	global_load_dword v2, v0, s[14:15] sc1
	s_add_i32 s0, s0, 1
	s_mov_b64 s[28:29], -1
	s_waitcnt vmcnt(0)
	v_cmp_ge_u32_e32 vcc, v2, v1
	s_orn2_b64 s[20:21], vcc, exec
	s_branch .LBB0_1599

; DI unsigned xb_ld(unsigned* p)              { return __hip_atomic_load(p, __ATOMIC_RELAXED, __HIP_MEMORY_SCOPE_AGENT); }
; DI unsigned xb_add(unsigned* p, unsigned v) { return __hip_atomic_fetch_add(p, v, __ATOMIC_RELAXED, __HIP_MEMORY_SCOPE_AGENT); }
; #define XB_SPIN(cond, bar) do { unsigned _sp = 0; while (cond) { __builtin_amdgcn_s_sleep(1); \
;     if ((++_sp & 255u) == 0u) { if (xb_ld(&(bar)[XB_TMO])) break; if (_sp > XB_SPIN_CAP) { atomicAdd(&(bar)[XB_TMO], 1u); break; } } } } while (0)
; DI void xcd_barrier(const XcdBarrier& b) {
;     ...
;       __builtin_amdgcn_fence(__ATOMIC_RELEASE, "agent");
;       asm volatile("s_waitcnt vmcnt(0)" ::: "memory");
;       const unsigned og = xb_add(&bar[XB_TOP], 1u);
;       const unsigned tg = og / nx;
;       if (og + 1u == (tg + 1u) * nx) xb_add(&bar[XB_TOPGEN], 1u);
;       else XB_SPIN(xb_ld(&bar[XB_TOPGEN]) == tg, bar);
.LBB0_1613:
	s_or_b64 exec, exec, s[10:11]
	v_cvt_f32_u32_e32 v3, v0
	s_waitcnt vmcnt(0)
	v_readfirstlane_b32 s0, v2
	s_add_u32 s10, s22, 0x1c103500
	s_addc_u32 s11, s23, 0
	v_rcp_iflag_f32_e32 v3, v3
	v_add_u32_e32 v1, s0, v1
	v_add_u32_e32 v4, 1, v1
	s_mov_b64 s[12:13], 0
	v_mul_f32_e32 v2, 0x4f7ffffe, v3
	v_cvt_u32_f32_e32 v2, v2
	v_sub_u32_e32 v3, 0, v0
	v_mul_lo_u32 v3, v3, v2
	v_mul_hi_u32 v3, v2, v3
	v_add_u32_e32 v2, v2, v3
	v_mul_hi_u32 v2, v1, v2
	v_mul_lo_u32 v3, v2, v0
	v_sub_u32_e32 v1, v1, v3
	v_add_u32_e32 v5, 1, v2
	v_cmp_ge_u32_e32 vcc, v1, v0
	v_sub_u32_e32 v3, v1, v0
	s_nop 0
	v_cndmask_b32_e32 v2, v2, v5, vcc
	v_cndmask_b32_e32 v1, v1, v3, vcc
	v_add_u32_e32 v3, 1, v2
	v_cmp_ge_u32_e32 vcc, v1, v0
	s_nop 1
	v_cndmask_b32_e32 v2, v2, v3, vcc
	v_mul_lo_u32 v1, v0, v2
	v_add_u32_e32 v0, v1, v0
	v_cmp_ne_u32_e32 vcc, v4, v0
	v_mov_b32_e32 v2, v0
	v_mov_b64_e32 v[0:1], s[10:11]
	s_and_saveexec_b64 s[8:9], vcc
	s_cbranch_execz .LBB0_1625
	v_mov_b32_e32 v0, 0
	global_load_dword v1, v0, s[10:11] offset:-256 sc1
	s_mov_b64 s[16:17], 0
	s_waitcnt vmcnt(0)
	v_cmp_lt_u32_e32 vcc, v1, v2
	s_and_saveexec_b64 s[14:15], vcc
	s_cbranch_execz .LBB0_1624
	s_add_u32 s12, s22, 0x1c100200
	s_addc_u32 s13, s23, 0
	s_mov_b32 s0, 1
	s_branch .LBB0_1617

; DI unsigned xb_ld(unsigned* p)              { return __hip_atomic_load(p, __ATOMIC_RELAXED, __HIP_MEMORY_SCOPE_AGENT); }
; DI unsigned xb_add(unsigned* p, unsigned v) { return __hip_atomic_fetch_add(p, v, __ATOMIC_RELAXED, __HIP_MEMORY_SCOPE_AGENT); }
; #define XB_SPIN(cond, bar) do { unsigned _sp = 0; while (cond) { __builtin_amdgcn_s_sleep(1); \
;     if ((++_sp & 255u) == 0u) { if (xb_ld(&(bar)[XB_TMO])) break; if (_sp > XB_SPIN_CAP) { atomicAdd(&(bar)[XB_TMO], 1u); break; } } } } while (0)
; DI void xcd_barrier(const XcdBarrier& b) {
;     ...
;       const unsigned og = xb_add(&bar[XB_TOP], 1u);
;       const unsigned tg = og / nx;
;       if (og + 1u == (tg + 1u) * nx) xb_add(&bar[XB_TOPGEN], 1u);
;       else XB_SPIN(xb_ld(&bar[XB_TOPGEN]) == tg, bar);
.LBB0_1621:
	global_load_dword v1, v0, s[10:11] offset:-256 sc1
	s_add_i32 s0, s0, 1
	s_mov_b64 s[20:21], -1
	s_waitcnt vmcnt(0)
	v_cmp_ge_u32_e32 vcc, v1, v2
	s_orn2_b64 s[36:37], vcc, exec
	s_branch .LBB0_1616

; DI unsigned xb_ld(unsigned* p)              { return __hip_atomic_load(p, __ATOMIC_RELAXED, __HIP_MEMORY_SCOPE_AGENT); }
; DI unsigned xb_add(unsigned* p, unsigned v) { return __hip_atomic_fetch_add(p, v, __ATOMIC_RELAXED, __HIP_MEMORY_SCOPE_AGENT); }
; #define XB_SPIN(cond, bar) do { unsigned _sp = 0; while (cond) { __builtin_amdgcn_s_sleep(1); \
;     if ((++_sp & 255u) == 0u) { if (xb_ld(&(bar)[XB_TMO])) break; if (_sp > XB_SPIN_CAP) { atomicAdd(&(bar)[XB_TMO], 1u); break; } } } } while (0)
; DI void xcd_barrier(const XcdBarrier& b) {
;     ...
;     unsigned nloc = b.st[0], nx = b.st[1];
;     if (nloc == 0u) { xcd_barrier_complete(bar, b.x, nloc, nx); b.st[0] = nloc; b.st[1] = nx; }
;     const unsigned old = xb_add(&bar[XB_XSUB(b.x)], 1u);
;     const unsigned gen = old / nloc;
;     if (old + 1u == (gen + 1u) * nloc) {
;       __builtin_amdgcn_fence(__ATOMIC_RELEASE, "agent");
;       asm volatile("s_waitcnt vmcnt(0)" ::: "memory");
;       const unsigned og = xb_add(&bar[XB_TOP], 1u);
;       const unsigned tg = og / nx;
;       if (og + 1u == (tg + 1u) * nx) xb_add(&bar[XB_TOPGEN], 1u);
;       else XB_SPIN(xb_ld(&bar[XB_TOPGEN]) == tg, bar);
;       __builtin_amdgcn_fence(__ATOMIC_ACQUIRE, "agent");
;       xb_add(&bar[XB_XGEN(b.x)], 1u);
;       asm volatile("s_waitcnt vmcnt(0)" ::: "memory");
;     } else {
;       XB_SPIN(xb_ld(&bar[XB_XGEN(b.x)]) == gen, bar);
.LBB0_1670:
	s_or_b64 exec, exec, s[8:9]
	v_cvt_f32_u32_e32 v4, v2
	s_waitcnt vmcnt(0)
	v_readfirstlane_b32 s0, v3
	v_sub_u32_e32 v3, 0, v2
	v_rcp_iflag_f32_e32 v4, v4
	v_add_u32_e32 v5, s0, v1
	v_mul_f32_e32 v4, 0x4f7ffffe, v4
	v_cvt_u32_f32_e32 v4, v4
	v_mul_lo_u32 v1, v3, v4
	v_mul_hi_u32 v1, v4, v1
	v_add_u32_e32 v1, v4, v1
	v_mul_hi_u32 v1, v5, v1
	v_mul_lo_u32 v3, v1, v2
	v_sub_u32_e32 v3, v5, v3
	v_add_u32_e32 v4, 1, v1
	v_cmp_ge_u32_e32 vcc, v3, v2
	s_nop 1
	v_cndmask_b32_e32 v1, v1, v4, vcc
	v_sub_u32_e32 v4, v3, v2
	v_cndmask_b32_e32 v3, v3, v4, vcc
	v_add_u32_e32 v4, 1, v1
	v_cmp_ge_u32_e32 vcc, v3, v2
	v_add_u32_e32 v3, 1, v5
	s_nop 0
	v_cndmask_b32_e32 v1, v1, v4, vcc
	v_mul_lo_u32 v4, v2, v1
	v_add_u32_e32 v2, v4, v2
	v_cmp_ne_u32_e32 vcc, v3, v2
	s_and_saveexec_b64 s[0:1], vcc
	s_xor_b64 s[6:7], exec, s[0:1]
	s_cbranch_execz .LBB0_1684
	s_waitcnt lgkmcnt(0)
	v_add_u32_e32 v1, 1, v1
	s_add_u32 s12, s22, 0x1c103400
	s_addc_u32 s13, s23, 0
	v_mul_lo_u32 v1, v1, v0
	v_mov_b32_e32 v0, 0
	global_load_dword v0, v0, s[12:13] sc1
	s_waitcnt vmcnt(0)
	v_cmp_lt_u32_e32 vcc, v0, v1
	s_and_saveexec_b64 s[8:9], vcc
	s_cbranch_execz .LBB0_1683
	s_add_u32 s10, s22, 0x1c100200
	s_addc_u32 s11, s23, 0
	s_mov_b32 s0, 1
	s_mov_b64 s[14:15], 0
	v_mov_b32_e32 v0, 0
	s_branch .LBB0_1674

; DI unsigned xb_ld(unsigned* p)              { return __hip_atomic_load(p, __ATOMIC_RELAXED, __HIP_MEMORY_SCOPE_AGENT); }
; #define XB_SPIN(cond, bar) do { unsigned _sp = 0; while (cond) { __builtin_amdgcn_s_sleep(1); \
;     if ((++_sp & 255u) == 0u) { if (xb_ld(&(bar)[XB_TMO])) break; if (_sp > XB_SPIN_CAP) { atomicAdd(&(bar)[XB_TMO], 1u); break; } } } } while (0)
; DI void xcd_barrier(const XcdBarrier& b) {
;     ...
;     } else {
;       XB_SPIN(xb_ld(&bar[XB_XGEN(b.x)]) == gen, bar);
.LBB0_1678:
	global_load_dword v2, v0, s[12:13] sc1
	s_add_i32 s0, s0, 1
	s_mov_b64 s[20:21], -1
	s_waitcnt vmcnt(0)
	v_cmp_ge_u32_e32 vcc, v2, v1
	s_orn2_b64 s[18:19], vcc, exec
	s_branch .LBB0_1673

; DI unsigned xb_ld(unsigned* p)              { return __hip_atomic_load(p, __ATOMIC_RELAXED, __HIP_MEMORY_SCOPE_AGENT); }
; DI unsigned xb_add(unsigned* p, unsigned v) { return __hip_atomic_fetch_add(p, v, __ATOMIC_RELAXED, __HIP_MEMORY_SCOPE_AGENT); }
; #define XB_SPIN(cond, bar) do { unsigned _sp = 0; while (cond) { __builtin_amdgcn_s_sleep(1); \
;     if ((++_sp & 255u) == 0u) { if (xb_ld(&(bar)[XB_TMO])) break; if (_sp > XB_SPIN_CAP) { atomicAdd(&(bar)[XB_TMO], 1u); break; } } } } while (0)
; DI void xcd_barrier(const XcdBarrier& b) {
;     ...
;       __builtin_amdgcn_fence(__ATOMIC_RELEASE, "agent");
;       asm volatile("s_waitcnt vmcnt(0)" ::: "memory");
;       const unsigned og = xb_add(&bar[XB_TOP], 1u);
;       const unsigned tg = og / nx;
;       if (og + 1u == (tg + 1u) * nx) xb_add(&bar[XB_TOPGEN], 1u);
;       else XB_SPIN(xb_ld(&bar[XB_TOPGEN]) == tg, bar);
.LBB0_1687:
	s_or_b64 exec, exec, s[8:9]
	v_cvt_f32_u32_e32 v3, v0
	s_waitcnt vmcnt(0)
	v_readfirstlane_b32 s0, v2
	s_add_u32 s8, s22, 0x1c103500
	s_addc_u32 s9, s23, 0
	v_rcp_iflag_f32_e32 v3, v3
	v_add_u32_e32 v1, s0, v1
	v_add_u32_e32 v4, 1, v1
	s_mov_b64 s[10:11], 0
	v_mul_f32_e32 v2, 0x4f7ffffe, v3
	v_cvt_u32_f32_e32 v2, v2
	v_sub_u32_e32 v3, 0, v0
	v_mul_lo_u32 v3, v3, v2
	v_mul_hi_u32 v3, v2, v3
	v_add_u32_e32 v2, v2, v3
	v_mul_hi_u32 v2, v1, v2
	v_mul_lo_u32 v3, v2, v0
	v_sub_u32_e32 v1, v1, v3
	v_add_u32_e32 v5, 1, v2
	v_cmp_ge_u32_e32 vcc, v1, v0
	v_sub_u32_e32 v3, v1, v0
	s_nop 0
	v_cndmask_b32_e32 v2, v2, v5, vcc
	v_cndmask_b32_e32 v1, v1, v3, vcc
	v_add_u32_e32 v3, 1, v2
	v_cmp_ge_u32_e32 vcc, v1, v0
	s_nop 1
	v_cndmask_b32_e32 v2, v2, v3, vcc
	v_mul_lo_u32 v1, v0, v2
	v_add_u32_e32 v0, v1, v0
	v_cmp_ne_u32_e32 vcc, v4, v0
	v_mov_b32_e32 v2, v0
	v_mov_b64_e32 v[0:1], s[8:9]
	s_and_saveexec_b64 s[6:7], vcc
	s_cbranch_execz .LBB0_1699
	v_mov_b32_e32 v0, 0
	global_load_dword v1, v0, s[8:9] offset:-256 sc1
	s_mov_b64 s[14:15], 0
	s_waitcnt vmcnt(0)
	v_cmp_lt_u32_e32 vcc, v1, v2
	s_and_saveexec_b64 s[12:13], vcc
	s_cbranch_execz .LBB0_1698
	s_add_u32 s10, s22, 0x1c100200
	s_addc_u32 s11, s23, 0
	s_mov_b32 s0, 1
	s_branch .LBB0_1691

; DI unsigned xb_ld(unsigned* p)              { return __hip_atomic_load(p, __ATOMIC_RELAXED, __HIP_MEMORY_SCOPE_AGENT); }
; DI unsigned xb_add(unsigned* p, unsigned v) { return __hip_atomic_fetch_add(p, v, __ATOMIC_RELAXED, __HIP_MEMORY_SCOPE_AGENT); }
; #define XB_SPIN(cond, bar) do { unsigned _sp = 0; while (cond) { __builtin_amdgcn_s_sleep(1); \
;     if ((++_sp & 255u) == 0u) { if (xb_ld(&(bar)[XB_TMO])) break; if (_sp > XB_SPIN_CAP) { atomicAdd(&(bar)[XB_TMO], 1u); break; } } } } while (0)
; DI void xcd_barrier(const XcdBarrier& b) {
;     ...
;       const unsigned og = xb_add(&bar[XB_TOP], 1u);
;       const unsigned tg = og / nx;
;       if (og + 1u == (tg + 1u) * nx) xb_add(&bar[XB_TOPGEN], 1u);
;       else XB_SPIN(xb_ld(&bar[XB_TOPGEN]) == tg, bar);
.LBB0_1695:
	global_load_dword v1, v0, s[8:9] offset:-256 sc1
	s_add_i32 s0, s0, 1
	s_mov_b64 s[18:19], -1
	s_waitcnt vmcnt(0)
	v_cmp_ge_u32_e32 vcc, v1, v2
	s_orn2_b64 s[22:23], vcc, exec
	s_branch .LBB0_1690
